# in-proj panel order: gelu panel 0 and raw panel 11 swapped between workgroup classes (balances the forget-gate class)
# speedup vs baseline: 1.0173x; 1.0057x over previous
.LBB0_249:
	v_writelane_b32 v253, s80, 2
	s_nop 1
	v_writelane_b32 v253, s81, 3
	v_writelane_b32 v253, s76, 4
	s_nop 1
	v_writelane_b32 v253, s77, 5
	s_or_b64 exec, exec, s[4:5]
	s_cmpk_lt_i32 s90, 0x400
	s_cselect_b64 s[4:5], -1, 0
	v_writelane_b32 v253, s4, 6
	s_ashr_i32 s66, s90, 31
	s_ashr_i32 s92, s60, 31
	v_writelane_b32 v253, s5, 7
	s_lshr_b32 s4, s66, 29
	s_add_i32 s4, s90, s4
	s_ashr_i32 s9, s4, 3
	s_and_b32 s4, s4, -8
	s_sub_i32 s10, s90, s4
	s_lshl_b32 s11, s10, 7
	s_cmp_eq_u32 s3, 15
	s_cselect_b64 s[4:5], -1, 0
	v_writelane_b32 v253, s4, 8
	s_cmp_eq_u32 s3, 14
	s_mul_i32 s8, s61, s60
	v_writelane_b32 v253, s5, 9
	s_cselect_b64 s[4:5], -1, 0
	v_writelane_b32 v253, s4, 10
	s_cmp_eq_u32 s3, 13
	s_mul_i32 s12, s10, 0x81
	v_writelane_b32 v253, s5, 11
	s_cselect_b64 s[4:5], -1, 0
	v_writelane_b32 v253, s4, 12
	s_cmp_eq_u32 s3, 12
	s_mul_i32 s96, s8, s2
	v_writelane_b32 v253, s5, 13
	s_cselect_b64 s[4:5], -1, 0
	v_writelane_b32 v253, s4, 14
	s_cmp_eq_u32 s3, 11
	v_lshlrev_b64 v[0:1], 2, v[0:1]
	v_writelane_b32 v253, s5, 15
	s_cselect_b64 s[4:5], -1, 0
	v_writelane_b32 v253, s4, 16
	s_cmp_eq_u32 s3, 10
	v_mov_b32_e32 v191, 0
	v_writelane_b32 v253, s5, 17
	s_cselect_b64 s[4:5], -1, 0
	v_writelane_b32 v253, s4, 18
	s_cmp_eq_u32 s3, 9
	s_mov_b32 s81, 0
	v_writelane_b32 v253, s5, 19
	s_cselect_b64 s[4:5], -1, 0
	v_writelane_b32 v253, s4, 20
	s_cmp_eq_u32 s3, 8
	s_movk_i32 s33, 0x200
	v_writelane_b32 v253, s5, 21
	s_cselect_b64 s[4:5], -1, 0
	v_writelane_b32 v253, s4, 22
	s_cmp_eq_u32 s3, 7
	s_movk_i32 s65, 0x2000
	v_writelane_b32 v253, s5, 23
	s_cselect_b64 s[4:5], -1, 0
	v_writelane_b32 v253, s4, 24
	s_cmp_eq_u32 s3, 6
	s_movk_i32 s82, 0x6000
	v_writelane_b32 v253, s5, 25
	s_cselect_b64 s[4:5], -1, 0
	v_writelane_b32 v253, s4, 26
	s_cmp_eq_u32 s3, 5
	v_mov_b32_e32 v192, 0x358637bd
	v_writelane_b32 v253, s5, 27
	s_cselect_b64 s[4:5], -1, 0
	v_writelane_b32 v253, s4, 28
	s_cmp_eq_u32 s3, 4
	v_mov_b32_e32 v185, 0x3ecc95a3
	v_writelane_b32 v253, s5, 29
	s_cselect_b64 s[4:5], -1, 0
	v_writelane_b32 v253, s4, 30
	s_cmp_eq_u32 s3, 3
	v_mov_b32_e32 v193, 1
	v_writelane_b32 v253, s5, 31
	s_cselect_b64 s[4:5], -1, 0
	v_writelane_b32 v253, s4, 32
	s_cmp_eq_u32 s3, 2
	v_mov_b64_e32 v[194:195], 0x400
	v_writelane_b32 v253, s5, 33
	s_cselect_b64 s[4:5], -1, 0
	v_writelane_b32 v253, s4, 34
	s_cmp_eq_u32 s3, 1
	v_mov_b64_e32 v[196:197], 0x3ff
	v_writelane_b32 v253, s5, 35
	s_cselect_b64 s[4:5], -1, 0
	v_writelane_b32 v253, s4, 36
	s_cmp_eq_u32 s3, 0
	v_mov_b32_e32 v224, 0x3e38aa3b
	v_writelane_b32 v253, s5, 37
	s_cselect_b64 s[4:5], -1, 0
	v_writelane_b32 v253, s4, 38
	s_cmpk_lt_i32 s78, 0x200
	v_mov_b32_e32 v225, 0x41b17218
	v_writelane_b32 v253, s5, 39
	s_cselect_b64 s[4:5], -1, 0
	s_lshl_b32 s72, s60, 1
	v_writelane_b32 v253, s4, 40
	s_cmpk_lt_i32 s78, 0x100
	v_mov_b32_e32 v226, 0x7f800000
	v_writelane_b32 v253, s5, 41
	s_cselect_b64 s[4:5], -1, 0
	v_writelane_b32 v253, s4, 42
	s_cmp_lt_i32 s78, 32
	v_mbcnt_hi_u32_b32 v227, -1, v78
	v_writelane_b32 v253, s5, 43
	s_cselect_b64 s[4:5], -1, 0
	v_writelane_b32 v253, s4, 44
	s_cmpk_eq_i32 s60, 0x100
	v_mov_b32_e32 v228, 0xff800000
	v_writelane_b32 v253, s5, 45
	s_cselect_b64 s[4:5], -1, 0
	v_writelane_b32 v253, s4, 46
	s_cmpk_lg_i32 s60, 0x100
	v_mov_b32_e32 v236, v191
	v_writelane_b32 v253, s5, 47
	s_cselect_b64 s[4:5], -1, 0
	v_writelane_b32 v253, s4, 48
	s_cmpk_lt_i32 s90, 0x100
	v_mov_b32_e32 v237, v191
	v_writelane_b32 v253, s5, 49
	s_cselect_b64 s[4:5], -1, 0
	v_writelane_b32 v253, s4, 50
	s_lshl_b32 s3, s10, 5
	v_mov_b64_e32 v[198:199], 0x100
	v_writelane_b32 v253, s5, 51
	s_getpc_b64 s[4:5]
	s_add_u32 s4, s4, g_ctl@rel32@lo+9220
	s_addc_u32 s5, s5, g_ctl@rel32@hi+9228
	s_getpc_b64 s[6:7]
	s_add_u32 s6, s6, g_ctl@rel32@lo+5124
	s_addc_u32 s7, s7, g_ctl@rel32@hi+5132
	s_cmp_lt_i32 s10, 0
	s_mul_i32 s10, s10, 33
	s_cselect_b32 s2, s12, s11
	s_cselect_b32 s3, s10, s3
	s_add_i32 s2, s2, s9
	v_lshl_add_u64 v[188:189], s[4:5], 0, v[0:1]
	s_ashr_i32 s4, s2, 31
	s_lshr_b32 s4, s4, 25
	s_add_i32 s4, s2, s4
	s_ashr_i32 s5, s4, 7
	s_and_b32 s4, s4, 0xff80
	s_sub_i32 s4, s2, s4
	s_bfe_i32 s2, s4, 0x80000
	s_bfe_u32 s2, s2, 0x3000c
	v_lshl_add_u64 v[186:187], s[6:7], 0, v[0:1]
	s_add_i32 s6, s4, s2
	s_bfe_i32 s2, s6, 0x80000
	s_and_b32 s6, s6, 0xf8
	s_sub_i32 s4, s4, s6
	s_lshl_b32 s5, s5, 3
	s_sext_i32_i16 s7, s2
	s_sext_i32_i8 s4, s4
	s_add_i32 s8, s5, s4
	s_ashr_i32 s4, s7, 3
	s_mov_b32 s100, 0x7654321b
	s_mov_b32 s101, 0xfedc0a98
	s_lshl_b32 s4, s4, 2
	s_lshr_b64 s[100:101], s[100:101], s4
	s_and_b32 s4, s100, 15
	s_add_i32 s3, s3, s9
	v_writelane_b32 v253, s4, 52
	s_ashr_i32 s4, s3, 31
	s_lshr_b32 s4, s4, 27
	s_add_i32 s4, s3, s4
	s_ashr_i32 s5, s4, 5
	s_and_b32 s4, s4, 0xffe0
	s_sub_i32 s3, s3, s4
	s_bfe_i32 s4, s3, 0x80000
	s_bfe_u32 s4, s4, 0x3000c
	s_add_i32 s6, s3, s4
	s_bfe_i32 s4, s6, 0x80000
	s_and_b32 s6, s6, 0xf8
	s_sub_i32 s3, s3, s6
	s_lshr_b32 s2, s7, 3
	s_mov_b32 s100, 0x7654321b
	s_mov_b32 s101, 0xfedc0a98
	s_lshl_b32 s2, s2, 2
	s_lshr_b64 s[100:101], s[100:101], s2
	s_and_b32 s2, s100, 15
	s_lshl_b32 s5, s5, 3
	s_sext_i32_i16 s7, s4
	s_sext_i32_i8 s3, s3
	s_add_i32 s10, s5, s3
	s_ashr_i32 s3, s7, 3
	v_writelane_b32 v253, s3, 53
	s_mov_b32 s6, s8
	s_lshr_b32 s4, s7, 3
	s_ashr_i32 s9, s8, 31
	v_writelane_b32 v253, s6, 54
	s_bfe_i64 s[2:3], s[2:3], 0x100000
	s_lshl_b64 s[2:3], s[2:3], 19
	v_writelane_b32 v253, s7, 55
	s_lshl_b64 s[6:7], s[8:9], 19
	v_writelane_b32 v253, s6, 56
	s_ashr_i32 s11, s10, 31
	s_ashr_i32 s79, s78, 31
	v_writelane_b32 v253, s7, 57
	v_writelane_b32 v253, s2, 58
	s_lshl_b32 s87, s60, 2
	v_mov_b64_e32 v[200:201], 0xff
	v_writelane_b32 v253, s3, 59
	s_mov_b32 s2, s10
	v_writelane_b32 v253, s2, 60
	s_mov_b32 s97, 0x18000
	s_mov_b32 s88, 0x1a000
	v_writelane_b32 v253, s3, 61
	s_lshl_b64 s[2:3], s[10:11], 19
	v_writelane_b32 v253, s2, 62
	s_mov_b32 s89, 0x8000
	s_mov_b32 s91, 0x1c000
	v_writelane_b32 v253, s3, 63
	s_bfe_i64 s[2:3], s[4:5], 0x100000
	s_lshl_b64 s[2:3], s[2:3], 19
	v_writelane_b32 v252, s2, 0
	s_mov_b32 s93, 0x800000
	s_mov_b32 s94, 0xbfb8aa3b
	v_writelane_b32 v252, s3, 1
	s_lshl_b32 s2, s78, 7
	v_writelane_b32 v252, s2, 2
	s_lshl_b32 s2, s60, 8
	v_writelane_b32 v252, s2, 3
	s_lshl_b32 s2, s78, 1
	v_writelane_b32 v252, s2, 4
	s_lshl_b64 s[2:3], s[78:79], 14
	s_add_u32 s2, s2, 0x1800000
	v_writelane_b32 v252, s2, 5
	s_addc_u32 s2, s3, 0
	s_ashr_i32 s73, s72, 31
	v_writelane_b32 v252, s2, 6
	s_lshl_b64 s[2:3], s[72:73], 14
	v_writelane_b32 v252, s2, 7
	s_mov_b32 s95, 0x3f317217
	s_mov_b32 s62, 0x7f800000
	v_writelane_b32 v252, s3, 8
	s_mov_b32 s2, s78
	v_writelane_b32 v252, s2, 9
	s_movk_i32 s70, 0x1e00
	s_movk_i32 s71, 0x90
	v_writelane_b32 v252, s3, 10
	s_lshl_b64 s[2:3], s[78:79], 8
	s_add_u32 s2, s2, 0x1600000
	v_writelane_b32 v252, s2, 11
	s_addc_u32 s2, s3, 0
	v_writelane_b32 v252, s2, 12
	s_add_i32 s2, 0, 0x23fc0
	v_writelane_b32 v252, s2, 13
	s_add_i32 s2, 0, 0x23fc4
	v_writelane_b32 v252, s2, 14
	s_add_i32 s2, 0, 0x4400
	v_writelane_b32 v252, s2, 15
	s_add_i32 s2, 0, 0x15c00
	v_writelane_b32 v252, s2, 16
	s_add_i32 s2, 0, 0x20800
	v_writelane_b32 v252, s2, 17
	s_lshl_b64 s[2:3], s[72:73], 8
	v_writelane_b32 v252, s2, 18
	s_movk_i32 s79, 0x4000
	s_mov_b32 s64, 0xb2a5705f
	s_mov_b32 s58, 0x42ce8ed0
	s_mov_b32 s59, 0xc2b17218
	s_mov_b32 s77, 0x3f2aaaab
	s_mov_b32 s78, 0x3f317218
	s_mov_b32 s63, 0x33800000
	s_movk_i32 s76, 0x1000
	s_mov_b32 s4, 0x9000
	s_mov_b32 s9, 0xb000
	s_mov_b32 s5, 0xf000
	s_mov_b32 s6, 0x11000
	s_mov_b32 s7, 0x13000
	s_mov_b32 s86, 0x15000
	s_mov_b32 s61, 0x17000
	v_writelane_b32 v252, s3, 19
	s_movk_i32 s73, 0x3000
	s_mov_b32 s67, 0xa000
	s_mov_b64 s[14:15], -1
	s_mov_b64 s[2:3], 0
	s_mov_b64 s[84:85], 0x80
	s_mov_b32 s8, 0x3c800000
	s_mov_b32 s16, s81
	s_barrier
	s_branch .LBB0_253

.LBB0_265:
	s_mov_b32 s2, 0x7654321b
	s_mov_b32 s3, 0xfedc0a98
	s_lshl_b32 s22, s22, 2
	s_lshr_b64 s[2:3], s[2:3], s22
	s_and_b32 s22, s2, 15
	s_ashr_i32 s25, s24, 31
	s_lshl_b64 s[26:27], s[24:25], 19
	s_add_u32 s26, s73, s26
	s_addc_u32 s27, s74, s27
	s_and_b64 s[28:29], s[40:41], exec
	s_cselect_b32 s25, s27, s31
	s_cselect_b32 s43, s26, s30
	s_ashr_i32 s23, s22, 31
	s_lshl_b64 s[28:29], s[22:23], 19
	s_add_u32 s28, s75, s28
	s_addc_u32 s29, s12, s29
	s_and_b64 s[36:37], s[40:41], exec
	s_cselect_b32 s23, s29, s35
	s_cselect_b32 s44, s28, s34
	s_add_u32 s30, s30, 0x40080
	s_addc_u32 s31, s31, 0
	s_add_u32 s45, s34, 0x100
	v_mov_b32_e32 v64, 0
	s_addc_u32 s46, s35, 0
	s_mov_b32 s47, -2
	v_mov_b32_e32 v65, v64
	v_mov_b32_e32 v66, v64
	v_mov_b32_e32 v67, v64
	v_mov_b32_e32 v68, v64
	v_mov_b32_e32 v69, v64
	v_mov_b32_e32 v70, v64
	v_mov_b32_e32 v71, v64
	v_mov_b32_e32 v72, v64
	v_mov_b32_e32 v73, v64
	v_mov_b32_e32 v74, v64
	v_mov_b32_e32 v75, v64
	v_mov_b32_e32 v76, v64
	v_mov_b32_e32 v77, v64
	v_mov_b32_e32 v78, v64
	v_mov_b32_e32 v79, v64
	v_mov_b32_e32 v80, v64
	v_mov_b32_e32 v81, v64
	v_mov_b32_e32 v82, v64
	v_mov_b32_e32 v83, v64
	v_mov_b32_e32 v84, v64
	v_mov_b32_e32 v85, v64
	v_mov_b32_e32 v86, v64
	v_mov_b32_e32 v87, v64
	v_mov_b32_e32 v88, v64
	v_mov_b32_e32 v89, v64
	v_mov_b32_e32 v90, v64
	v_mov_b32_e32 v91, v64
	v_mov_b32_e32 v92, v64
	v_mov_b32_e32 v93, v64
	v_mov_b32_e32 v94, v64
	v_mov_b32_e32 v95, v64
	v_mov_b32_e32 v0, v64
	v_mov_b32_e32 v1, v64
	v_mov_b32_e32 v2, v64
	v_mov_b32_e32 v3, v64
	v_mov_b32_e32 v4, v64
	v_mov_b32_e32 v5, v64
	v_mov_b32_e32 v6, v64
	v_mov_b32_e32 v7, v64
	v_mov_b32_e32 v8, v64
	v_mov_b32_e32 v9, v64
	v_mov_b32_e32 v10, v64
	v_mov_b32_e32 v11, v64
	v_mov_b32_e32 v12, v64
	v_mov_b32_e32 v13, v64
	v_mov_b32_e32 v14, v64
	v_mov_b32_e32 v15, v64
	v_mov_b32_e32 v16, v64
	v_mov_b32_e32 v17, v64
	v_mov_b32_e32 v18, v64
	v_mov_b32_e32 v19, v64
	v_mov_b32_e32 v20, v64
	v_mov_b32_e32 v21, v64
	v_mov_b32_e32 v22, v64
	v_mov_b32_e32 v23, v64
	v_mov_b32_e32 v24, v64
	v_mov_b32_e32 v25, v64
	v_mov_b32_e32 v26, v64
	v_mov_b32_e32 v27, v64
	v_mov_b32_e32 v28, v64
	v_mov_b32_e32 v29, v64
	v_mov_b32_e32 v30, v64
	v_mov_b32_e32 v31, v64
	v_mov_b32_e32 v96, v64
	v_mov_b32_e32 v97, v64
	v_mov_b32_e32 v98, v64
	v_mov_b32_e32 v99, v64
	v_mov_b32_e32 v100, v64
	v_mov_b32_e32 v101, v64
	v_mov_b32_e32 v102, v64
	v_mov_b32_e32 v103, v64
	v_mov_b32_e32 v104, v64
	v_mov_b32_e32 v105, v64
	v_mov_b32_e32 v106, v64
	v_mov_b32_e32 v107, v64
	v_mov_b32_e32 v108, v64
	v_mov_b32_e32 v109, v64
	v_mov_b32_e32 v110, v64
	v_mov_b32_e32 v111, v64
	v_mov_b32_e32 v112, v64
	v_mov_b32_e32 v113, v64
	v_mov_b32_e32 v114, v64
	v_mov_b32_e32 v115, v64
	v_mov_b32_e32 v116, v64
	v_mov_b32_e32 v117, v64
	v_mov_b32_e32 v118, v64
	v_mov_b32_e32 v119, v64
	v_mov_b32_e32 v120, v64
	v_mov_b32_e32 v121, v64
	v_mov_b32_e32 v122, v64
	v_mov_b32_e32 v123, v64
	v_mov_b32_e32 v124, v64
	v_mov_b32_e32 v125, v64
	v_mov_b32_e32 v126, v64
	v_mov_b32_e32 v127, v64
	v_mov_b32_e32 v32, v64
	v_mov_b32_e32 v33, v64
	v_mov_b32_e32 v34, v64
	v_mov_b32_e32 v35, v64
	v_mov_b32_e32 v36, v64
	v_mov_b32_e32 v37, v64
	v_mov_b32_e32 v38, v64
	v_mov_b32_e32 v39, v64
	v_mov_b32_e32 v40, v64
	v_mov_b32_e32 v41, v64
	v_mov_b32_e32 v42, v64
	v_mov_b32_e32 v43, v64
	v_mov_b32_e32 v44, v64
	v_mov_b32_e32 v45, v64
	v_mov_b32_e32 v46, v64
	v_mov_b32_e32 v47, v64
	v_mov_b32_e32 v48, v64
	v_mov_b32_e32 v49, v64
	v_mov_b32_e32 v50, v64
	v_mov_b32_e32 v51, v64
	v_mov_b32_e32 v52, v64
	v_mov_b32_e32 v53, v64
	v_mov_b32_e32 v54, v64
	v_mov_b32_e32 v55, v64
	v_mov_b32_e32 v56, v64
	v_mov_b32_e32 v57, v64
	v_mov_b32_e32 v58, v64
	v_mov_b32_e32 v59, v64
	v_mov_b32_e32 v60, v64
	v_mov_b32_e32 v61, v64
	v_mov_b32_e32 v62, v64
	v_mov_b32_e32 v63, v64
